# grid barrier: arriver 28 of each XCD starts an L2 write-back (buffer_wbl2 sc1) before polling, last arriver's release flush unchanged
# speedup vs baseline: 1.0013x; 1.0013x over previous
.LBB0_1500:
	s_or_b64 exec, exec, s[2:3]
	v_cvt_f32_u32_e32 v5, v3
	s_waitcnt vmcnt(0)
	v_readfirstlane_b32 s2, v4
	v_sub_u32_e32 v4, 0, v3
	v_rcp_iflag_f32_e32 v5, v5
	v_add_u32_e32 v6, s2, v1
	v_mul_f32_e32 v5, 0x4f7ffffe, v5
	v_cvt_u32_f32_e32 v5, v5
	v_mul_lo_u32 v1, v4, v5
	v_mul_hi_u32 v1, v5, v1
	v_add_u32_e32 v1, v5, v1
	v_mul_hi_u32 v1, v6, v1
	v_mul_lo_u32 v4, v1, v3
	v_sub_u32_e32 v4, v6, v4
	v_add_u32_e32 v5, 1, v1
	v_cmp_ge_u32_e32 vcc, v4, v3
	s_nop 1
	v_cndmask_b32_e32 v1, v1, v5, vcc
	v_sub_u32_e32 v5, v4, v3
	v_cndmask_b32_e32 v4, v4, v5, vcc
	v_add_u32_e32 v5, 1, v1
	v_cmp_ge_u32_e32 vcc, v4, v3
	v_add_u32_e32 v4, 1, v6
	s_nop 0
	v_cndmask_b32_e32 v1, v1, v5, vcc
	v_mul_lo_u32 v5, v3, v1
	v_add_u32_e32 v3, v5, v3
	v_cmp_ne_u32_e32 vcc, v4, v3
	s_and_saveexec_b64 s[2:3], vcc
	s_xor_b64 s[2:3], exec, s[2:3]
	s_cbranch_execz .LBB0_1514
	v_readlane_b32 s4, v254, 62
	v_readlane_b32 s5, v254, 63
	s_branch .Lxbf
.Lxbf_ret:
	s_nop 3
	global_load_dword v2, v0, s[4:5] sc1
	s_waitcnt vmcnt(0)
	v_cmp_eq_u32_e32 vcc, v2, v1
	s_and_saveexec_b64 s[4:5], vcc
	s_cbranch_execz .LBB0_1513
	s_mov_b32 s20, 1
	s_mov_b64 s[6:7], 0
	s_branch .LBB0_1504

.Lxbf:
	s_waitcnt lgkmcnt(0)
	v_add_u32_e32 v4, 28, v5
	v_cmp_eq_u32_e32 vcc, v6, v4
	s_cbranch_vccz .Lxbf_ret
	buffer_wbl2 sc1
	s_branch .Lxbf_ret
